# unit loops: next-unit index arithmetic uses shift/mask for the group-of-4 split instead of the float-reciprocal division
# baseline (speedup 1.0000x reference)
.LBB0_440:
	s_ashr_i32 s20, s20, 3
	s_add_i32 s20, s50, s20
	s_ashr_i32 s21, s20, 31
	s_lshr_b32 s21, s21, 28
	s_add_i32 s21, s20, s21
	s_ashr_i32 s22, s21, 4
	s_lshl_b32 s22, s22, 2
	s_sub_i32 s23, 0x80, s22
	s_min_i32 s23, s23, 4
	s_and_b32 s21, s21, -16
	s_sub_i32 s20, s20, s21
	s_ashr_i32 s88, s20, 2
	s_and_b32 s20, s20, 3
	s_add_i32 s89, s22, s20

.LBB0_485:
	s_add_i32 s89, s85, 1
	s_mul_i32 s20, s89, s67
	s_mul_hi_u32 s21, s89, s66
	s_add_i32 s21, s21, s20
	s_mul_i32 s20, s89, s66
	v_readlane_b32 s12, v247, 0
	v_readlane_b32 s13, v247, 1
	s_add_u32 s60, s20, s12
	s_addc_u32 s61, s21, s13
	v_cmp_gt_i64_e32 vcc, s[60:61], v[164:165]
	v_cmp_lt_i64_e64 s[54:55], s[60:61], v[174:175]
	s_cbranch_vccnz .LBB0_487
	s_ashr_i32 s20, s60, 31
	s_lshr_b32 s20, s20, 29
	s_add_i32 s20, s60, s20
	s_ashr_i32 s21, s20, 3
	s_and_b32 s20, s20, -8
	s_sub_i32 s20, s60, s20
	s_cmp_lt_i32 s20, 0
	s_movk_i32 s12, 0x161
	s_cselect_b32 s22, s12, 0x160
	s_mul_i32 s20, s20, s22
	s_add_i32 s20, s20, s21
	s_mul_hi_i32 s21, s20, 0x2e8ba2e9
	s_lshr_b32 s22, s21, 31
	s_ashr_i32 s21, s21, 4
	s_add_i32 s21, s21, s22
	s_lshl_b32 s22, s21, 2
	s_sub_i32 s23, 0x80, s22
	s_min_i32 s23, s23, 4
	s_mulk_i32 s21, 0x58
	s_sub_i32 s20, s20, s21
	s_ashr_i32 s50, s20, 2
	s_and_b32 s20, s20, 3
	s_add_i32 s56, s22, s20

.LBB0_602:
	s_ashr_i32 s20, s20, 3
	s_add_i32 s20, s42, s20
	s_ashr_i32 s21, s20, 31
	s_lshr_b32 s21, s21, 29
	s_add_i32 s21, s20, s21
	s_ashr_i32 s22, s21, 3
	s_lshl_b32 s22, s22, 2
	s_sub_i32 s23, 0x80, s22
	s_min_i32 s23, s23, 4
	s_and_b32 s21, s21, -8
	s_sub_i32 s20, s20, s21
	s_ashr_i32 s48, s20, 2
	s_and_b32 s20, s20, 3
	s_add_i32 s50, s22, s20

.LBB0_640:
	s_ashr_i32 s20, s20, 3
	s_add_i32 s20, s40, s20
	s_ashr_i32 s21, s20, 31
	s_lshr_b32 s21, s21, 28
	s_add_i32 s21, s20, s21
	s_ashr_i32 s22, s21, 4
	s_lshl_b32 s22, s22, 2
	s_sub_i32 s23, 0x80, s22
	s_min_i32 s23, s23, 4
	s_and_b32 s21, s21, -16
	s_sub_i32 s20, s20, s21
	s_ashr_i32 s48, s20, 2
	s_and_b32 s20, s20, 3
	s_add_i32 s50, s22, s20

.LBB0_776:
	s_ashr_i32 s20, s20, 3
	s_add_i32 s20, s60, s20
	s_ashr_i32 s21, s20, 31
	s_lshr_b32 s21, s21, 28
	s_add_i32 s21, s20, s21
	s_ashr_i32 s22, s21, 4
	s_lshl_b32 s22, s22, 2
	s_sub_i32 s23, 0x80, s22
	s_min_i32 s23, s23, 4
	s_and_b32 s21, s21, -16
	s_sub_i32 s20, s20, s21
	s_ashr_i32 s58, s20, 2
	s_and_b32 s20, s20, 3
	s_add_i32 s60, s22, s20

.LBB0_847:
	s_add_i32 s97, s85, 1
	s_mul_i32 s20, s97, s67
	s_mul_hi_u32 s21, s97, s66
	s_add_i32 s21, s21, s20
	s_mul_i32 s20, s97, s66
	v_readlane_b32 s12, v247, 0
	v_readlane_b32 s13, v247, 1
	s_add_u32 s76, s20, s12
	s_addc_u32 s77, s21, s13
	v_cmp_gt_i64_e32 vcc, s[76:77], v[166:167]
	v_cmp_lt_i64_e64 s[54:55], s[76:77], v[180:181]
	s_cbranch_vccnz .LBB0_849
	s_ashr_i32 s20, s76, 31
	s_lshr_b32 s20, s20, 29
	s_add_i32 s20, s76, s20
	s_ashr_i32 s21, s20, 3
	s_and_b32 s20, s20, -8
	s_sub_i32 s20, s76, s20
	s_cmp_lt_i32 s20, 0
	s_movk_i32 s12, 0x51
	s_cselect_b32 s68, s12, 0x50
	s_mul_i32 s20, s20, s68
	s_add_i32 s20, s20, s21
	s_mul_hi_i32 s21, s20, 0x66666667
	s_lshr_b32 s68, s21, 31
	s_ashr_i32 s21, s21, 3
	s_add_i32 s21, s21, s68
	s_lshl_b32 s69, s21, 2
	s_sub_i32 s68, 0x80, s69
	s_min_i32 s76, s68, 4
	s_mul_i32 s21, s21, 20
	s_sub_i32 s20, s20, s21
	s_ashr_i32 s68, s20, 2
	s_and_b32 s20, s20, 3
	s_add_i32 s78, s69, s20
